# P9 epilogue: hoist the 16 second-half residual loads (counted vmcnt) instead of 16 serialized load-wait-store steps
# speedup vs baseline: 1.0044x; 1.0044x over previous
;     __device__ __forceinline__ void fused(f32x4 (&acc)[2][2][4][2], const Unit& u, int wr, int wc, int fr, int fq, PG8_LAS unsigned char* lds, int wid, int lane) const {
;     ...
;         const bool bad = st.run(acc, u, wr, wc, fr, fq, lds, wid, lane) || poison != 0u;
;         const float qnan = __builtin_nanf("");
; #pragma unroll
;         for (int ai = 0; ai < 2; ++ai)
; #pragma unroll
;             for (int m = 0; m < 4; ++m) { const int r = ai * HALF + wr * 64 + m * 16 + fr; const f32x2v sr = S[r]; const size_t off = (size_t)(u.pm * BM + r) * ldc + col0;
; #pragma unroll
;                 for (int bj = 0; bj < 2; ++bj)
; #pragma unroll
;                     for (int n = 0; n < 2; ++n) { const f32x4 bs = ai == 0 ? pre[m][bj][n] : *(const f32x4*)(base + off + bj * HALF + n * 16); f32x4 o = bs + cvv[bj][n] * (acc[ai][bj][m][n] * sr.y);
;                         if (bad) o = (f32x4){qnan, qnan, qnan, qnan}; *(f32x4*)(out + off + bj * HALF + n * 16) = o; }
;                 if (m & 1) asm volatile("" ::: "memory"); }
.LBB0_1304:
	s_or_b64 exec, exec, s[2:3]
	v_lshl_add_u32 v0, v219, 3, 0
	s_waitcnt lgkmcnt(0)
	s_barrier
	v_add_u32_e32 v216, 0x2000, v0
	ds_read2_b64 v[220:223], v216 offset1:16
	s_waitcnt vmcnt(0) lgkmcnt(0)
	v_or_b32_e32 v217, v217, v218
	v_add_u32_e32 v0, s16, v219
	v_ashrrev_i32_e32 v1, 31, v0
	v_cmp_ne_u32_e32 vcc, 0, v217
	v_pk_mul_f32 v[128:129], v[128:129], v[220:221] op_sel:[0,1]
	v_pk_mul_f32 v[126:127], v[126:127], v[220:221] op_sel:[0,1]
	v_pk_fma_f32 v[128:129], v[144:145], v[128:129], v[208:209]
	v_pk_fma_f32 v[206:207], v[142:143], v[126:127], v[206:207]
	v_mov_b32_e32 v126, 0x7fc00000
	v_cndmask_b32_e32 v209, v129, v126, vcc
	v_cndmask_b32_e32 v208, v128, v126, vcc
	v_lshlrev_b64 v[128:129], 12, v[0:1]
	v_pk_mul_f32 v[120:121], v[120:121], v[220:221] op_sel:[0,1]
	v_pk_mul_f32 v[118:119], v[118:119], v[220:221] op_sel:[0,1]
	v_pk_mul_f32 v[112:113], v[112:113], v[220:221] op_sel:[0,1]
	v_pk_mul_f32 v[110:111], v[110:111], v[220:221] op_sel:[0,1]
	v_lshl_add_u64 v[128:129], s[76:77], 0, v[128:129]
	v_pk_fma_f32 v[118:119], v[134:135], v[118:119], v[198:199]
	v_pk_fma_f32 v[120:121], v[136:137], v[120:121], v[200:201]
	v_pk_fma_f32 v[110:111], v[130:131], v[110:111], v[194:195]
	v_pk_fma_f32 v[112:113], v[132:133], v[112:113], v[196:197]
	v_lshl_add_u64 v[128:129], v[128:129], 0, v[214:215]
	v_cndmask_b32_e32 v121, v121, v126, vcc
	v_cndmask_b32_e32 v120, v120, v126, vcc
	v_cndmask_b32_e32 v119, v119, v126, vcc
	v_cndmask_b32_e32 v118, v118, v126, vcc
	v_cndmask_b32_e32 v113, v113, v126, vcc
	v_cndmask_b32_e32 v112, v112, v126, vcc
	v_cndmask_b32_e32 v111, v111, v126, vcc
	v_cndmask_b32_e32 v110, v110, v126, vcc
	global_store_dwordx4 v[128:129], v[118:121], off offset:512
	global_store_dwordx4 v[128:129], v[110:113], off offset:576
	v_pk_mul_f32 v[124:125], v[124:125], v[220:221] op_sel:[0,1]
	v_add_u32_e32 v118, 16, v0
	v_pk_mul_f32 v[110:111], v[116:117], v[222:223] op_sel:[0,1]
	v_pk_mul_f32 v[112:113], v[114:115], v[222:223] op_sel:[0,1]
	v_ashrrev_i32_e32 v119, 31, v118
	v_pk_fma_f32 v[114:115], v[142:143], v[112:113], v[190:191]
	v_pk_fma_f32 v[110:111], v[144:145], v[110:111], v[192:193]
	v_pk_mul_f32 v[122:123], v[122:123], v[220:221] op_sel:[0,1]
	v_cndmask_b32_e32 v113, v111, v126, vcc
	v_cndmask_b32_e32 v112, v110, v126, vcc
	v_cndmask_b32_e32 v111, v115, v126, vcc
	v_cndmask_b32_e32 v110, v114, v126, vcc
	v_lshlrev_b64 v[114:115], 12, v[118:119]
	v_pk_mul_f32 v[108:109], v[108:109], v[222:223] op_sel:[0,1]
	v_pk_mul_f32 v[106:107], v[106:107], v[222:223] op_sel:[0,1]
	v_pk_mul_f32 v[104:105], v[104:105], v[222:223] op_sel:[0,1]
	v_pk_mul_f32 v[102:103], v[102:103], v[222:223] op_sel:[0,1]
	v_pk_mul_f32 v[96:97], v[96:97], v[222:223] op_sel:[0,1]
	v_pk_mul_f32 v[94:95], v[94:95], v[222:223] op_sel:[0,1]
	v_pk_fma_f32 v[122:123], v[138:139], v[122:123], v[202:203]
	v_pk_fma_f32 v[124:125], v[140:141], v[124:125], v[204:205]
	v_lshl_add_u64 v[114:115], s[76:77], 0, v[114:115]
	v_pk_fma_f32 v[106:107], v[138:139], v[106:107], v[186:187]
	v_pk_fma_f32 v[108:109], v[140:141], v[108:109], v[188:189]
	v_pk_fma_f32 v[102:103], v[134:135], v[102:103], v[182:183]
	v_pk_fma_f32 v[104:105], v[136:137], v[104:105], v[184:185]
	v_pk_fma_f32 v[94:95], v[130:131], v[94:95], v[178:179]
	v_pk_fma_f32 v[96:97], v[132:133], v[96:97], v[180:181]
	v_cndmask_b32_e32 v207, v207, v126, vcc
	v_cndmask_b32_e32 v206, v206, v126, vcc
	v_cndmask_b32_e32 v125, v125, v126, vcc
	v_cndmask_b32_e32 v124, v124, v126, vcc
	v_cndmask_b32_e32 v123, v123, v126, vcc
	v_cndmask_b32_e32 v122, v122, v126, vcc
	v_lshl_add_u64 v[114:115], v[114:115], 0, v[214:215]
	v_cndmask_b32_e32 v109, v109, v126, vcc
	v_cndmask_b32_e32 v108, v108, v126, vcc
	v_cndmask_b32_e32 v107, v107, v126, vcc
	v_cndmask_b32_e32 v106, v106, v126, vcc
	v_cndmask_b32_e32 v105, v105, v126, vcc
	v_cndmask_b32_e32 v104, v104, v126, vcc
	v_cndmask_b32_e32 v103, v103, v126, vcc
	v_cndmask_b32_e32 v102, v102, v126, vcc
	v_cndmask_b32_e32 v97, v97, v126, vcc
	v_cndmask_b32_e32 v96, v96, v126, vcc
	v_cndmask_b32_e32 v95, v95, v126, vcc
	v_cndmask_b32_e32 v94, v94, v126, vcc
	global_store_dwordx4 v[128:129], v[206:209], off
	global_store_dwordx4 v[128:129], v[122:125], off offset:64
	global_store_dwordx4 v[114:115], v[110:113], off
	global_store_dwordx4 v[114:115], v[106:109], off offset:64
	global_store_dwordx4 v[114:115], v[102:105], off offset:512
	global_store_dwordx4 v[114:115], v[94:97], off offset:576
	ds_read2_b64 v[94:97], v216 offset0:32 offset1:48
	v_add_u32_e32 v102, 32, v0
	v_ashrrev_i32_e32 v103, 31, v102
	v_lshlrev_b64 v[102:103], 12, v[102:103]
	v_lshl_add_u64 v[102:103], s[76:77], 0, v[102:103]
	s_waitcnt lgkmcnt(0)
;     __device__ __forceinline__ void fused(f32x4 (&acc)[2][2][4][2], const Unit& u, int wr, int wc, int fr, int fq, PG8_LAS unsigned char* lds, int wid, int lane) const {
;     ...
;             for (int m = 0; m < 4; ++m) { const int r = ai * HALF + wr * 64 + m * 16 + fr; const f32x2v sr = S[r]; const size_t off = (size_t)(u.pm * BM + r) * ldc + col0;
; #pragma unroll
;                 for (int bj = 0; bj < 2; ++bj)
; #pragma unroll
;                     for (int n = 0; n < 2; ++n) { const f32x4 bs = ai == 0 ? pre[m][bj][n] : *(const f32x4*)(base + off + bj * HALF + n * 16); f32x4 o = bs + cvv[bj][n] * (acc[ai][bj][m][n] * sr.y);
;                         if (bad) o = (f32x4){qnan, qnan, qnan, qnan}; *(f32x4*)(out + off + bj * HALF + n * 16) = o; }
	v_pk_mul_f32 v[88:89], v[88:89], v[94:95] op_sel:[0,1]
	v_pk_mul_f32 v[86:87], v[86:87], v[94:95] op_sel:[0,1]
	v_pk_mul_f32 v[80:81], v[80:81], v[94:95] op_sel:[0,1]
	v_pk_mul_f32 v[78:79], v[78:79], v[94:95] op_sel:[0,1]
	v_pk_fma_f32 v[86:87], v[134:135], v[86:87], v[166:167]
	v_pk_fma_f32 v[88:89], v[136:137], v[88:89], v[168:169]
	v_pk_fma_f32 v[78:79], v[130:131], v[78:79], v[162:163]
	v_pk_fma_f32 v[80:81], v[132:133], v[80:81], v[164:165]
	v_lshl_add_u64 v[102:103], v[102:103], 0, v[214:215]
	v_cndmask_b32_e32 v89, v89, v126, vcc
	v_cndmask_b32_e32 v88, v88, v126, vcc
	v_cndmask_b32_e32 v87, v87, v126, vcc
	v_cndmask_b32_e32 v86, v86, v126, vcc
	v_cndmask_b32_e32 v81, v81, v126, vcc
	v_cndmask_b32_e32 v80, v80, v126, vcc
	v_cndmask_b32_e32 v79, v79, v126, vcc
	v_cndmask_b32_e32 v78, v78, v126, vcc
	global_store_dwordx4 v[102:103], v[86:89], off offset:512
	global_store_dwordx4 v[102:103], v[78:81], off offset:576
	v_pk_mul_f32 v[76:77], v[76:77], v[96:97] op_sel:[0,1]
	v_add_u32_e32 v86, 48, v0
	v_pk_mul_f32 v[78:79], v[84:85], v[96:97] op_sel:[0,1]
	v_pk_mul_f32 v[80:81], v[82:83], v[96:97] op_sel:[0,1]
	v_ashrrev_i32_e32 v87, 31, v86
	v_pk_fma_f32 v[82:83], v[142:143], v[80:81], v[158:159]
	v_pk_fma_f32 v[78:79], v[144:145], v[78:79], v[160:161]
	v_pk_mul_f32 v[74:75], v[74:75], v[96:97] op_sel:[0,1]
	v_cndmask_b32_e32 v81, v79, v126, vcc
	v_cndmask_b32_e32 v80, v78, v126, vcc
	v_cndmask_b32_e32 v79, v83, v126, vcc
	v_cndmask_b32_e32 v78, v82, v126, vcc
	v_lshlrev_b64 v[82:83], 12, v[86:87]
	v_lshl_add_u64 v[82:83], s[76:77], 0, v[82:83]
	v_pk_fma_f32 v[74:75], v[138:139], v[74:75], v[154:155]
	v_pk_fma_f32 v[76:77], v[140:141], v[76:77], v[156:157]
	v_pk_mul_f32 v[100:101], v[100:101], v[94:95] op_sel:[0,1]
	v_pk_mul_f32 v[98:99], v[98:99], v[94:95] op_sel:[0,1]
	v_pk_mul_f32 v[92:93], v[92:93], v[94:95] op_sel:[0,1]
	v_pk_mul_f32 v[90:91], v[90:91], v[94:95] op_sel:[0,1]
	v_lshl_add_u64 v[82:83], v[82:83], 0, v[214:215]
	v_cndmask_b32_e32 v77, v77, v126, vcc
	v_cndmask_b32_e32 v76, v76, v126, vcc
	v_cndmask_b32_e32 v75, v75, v126, vcc
	v_cndmask_b32_e32 v74, v74, v126, vcc
	v_pk_mul_f32 v[72:73], v[72:73], v[96:97] op_sel:[0,1]
	v_pk_mul_f32 v[70:71], v[70:71], v[96:97] op_sel:[0,1]
	v_pk_mul_f32 v[68:69], v[68:69], v[96:97] op_sel:[0,1]
	v_pk_mul_f32 v[66:67], v[66:67], v[96:97] op_sel:[0,1]
	v_pk_fma_f32 v[98:99], v[142:143], v[98:99], v[174:175]
	v_pk_fma_f32 v[100:101], v[144:145], v[100:101], v[176:177]
	v_pk_fma_f32 v[90:91], v[138:139], v[90:91], v[170:171]
	v_pk_fma_f32 v[92:93], v[140:141], v[92:93], v[172:173]
	global_store_dwordx4 v[82:83], v[74:77], off offset:64
	v_pk_fma_f32 v[70:71], v[134:135], v[70:71], v[150:151]
	v_pk_fma_f32 v[72:73], v[136:137], v[72:73], v[152:153]
	v_pk_fma_f32 v[66:67], v[130:131], v[66:67], v[146:147]
	v_pk_fma_f32 v[68:69], v[132:133], v[68:69], v[148:149]
	v_add_u32_e32 v74, 0x80, v0
	v_cndmask_b32_e32 v101, v101, v126, vcc
	v_cndmask_b32_e32 v100, v100, v126, vcc
	v_cndmask_b32_e32 v99, v99, v126, vcc
	v_cndmask_b32_e32 v98, v98, v126, vcc
	v_cndmask_b32_e32 v93, v93, v126, vcc
	v_cndmask_b32_e32 v92, v92, v126, vcc
	v_cndmask_b32_e32 v91, v91, v126, vcc
	v_cndmask_b32_e32 v90, v90, v126, vcc
	v_cndmask_b32_e32 v73, v73, v126, vcc
	v_cndmask_b32_e32 v72, v72, v126, vcc
	v_cndmask_b32_e32 v71, v71, v126, vcc
	v_cndmask_b32_e32 v70, v70, v126, vcc
	v_cndmask_b32_e32 v69, v69, v126, vcc
	v_cndmask_b32_e32 v68, v68, v126, vcc
	v_cndmask_b32_e32 v67, v67, v126, vcc
	v_cndmask_b32_e32 v66, v66, v126, vcc
	v_ashrrev_i32_e32 v75, 31, v74
	global_store_dwordx4 v[102:103], v[98:101], off
	global_store_dwordx4 v[102:103], v[90:93], off offset:64
	global_store_dwordx4 v[82:83], v[78:81], off
	global_store_dwordx4 v[82:83], v[70:73], off offset:512
	global_store_dwordx4 v[82:83], v[66:69], off offset:576
	ds_read2_b64 v[88:91], v216 offset0:128 offset1:144
	ds_read2_b64 v[92:95], v216 offset0:160 offset1:176
	v_mov_b32_e32 v86, 0x10000
	v_mov_b32_e32 v87, 0
	v_add_u32_e32 v66, 0x80, v0
	v_ashrrev_i32_e32 v67, 31, v66
	v_lshlrev_b64 v[68:69], 12, v[66:67]
	v_lshl_add_u64 v[70:71], v[212:213], 0, v[68:69]
	v_lshl_add_u64 v[72:73], s[76:77], 0, v[68:69]
	v_lshl_add_u64 v[72:73], v[72:73], 0, v[214:215]
	global_load_dwordx4 v[146:149], v[70:71], off
	global_load_dwordx4 v[150:153], v[70:71], off offset:64
	global_load_dwordx4 v[154:157], v[70:71], off offset:512
	global_load_dwordx4 v[158:161], v[70:71], off offset:576
	v_lshl_add_u64 v[74:75], v[70:71], 0, v[86:87]
	v_lshl_add_u64 v[76:77], v[72:73], 0, v[86:87]
	global_load_dwordx4 v[162:165], v[74:75], off
	global_load_dwordx4 v[166:169], v[74:75], off offset:64
	global_load_dwordx4 v[170:173], v[74:75], off offset:512
	global_load_dwordx4 v[174:177], v[74:75], off offset:576
	v_lshl_add_u64 v[78:79], v[74:75], 0, v[86:87]
	v_lshl_add_u64 v[80:81], v[76:77], 0, v[86:87]
	global_load_dwordx4 v[178:181], v[78:79], off
	global_load_dwordx4 v[182:185], v[78:79], off offset:64
	global_load_dwordx4 v[186:189], v[78:79], off offset:512
	global_load_dwordx4 v[190:193], v[78:79], off offset:576
	v_lshl_add_u64 v[82:83], v[78:79], 0, v[86:87]
	v_lshl_add_u64 v[84:85], v[80:81], 0, v[86:87]
	global_load_dwordx4 v[194:197], v[82:83], off
	global_load_dwordx4 v[198:201], v[82:83], off offset:64
	global_load_dwordx4 v[202:205], v[82:83], off offset:512
	global_load_dwordx4 v[206:209], v[82:83], off offset:576
	s_waitcnt lgkmcnt(0)
;     __device__ __forceinline__ void fused(f32x4 (&acc)[2][2][4][2], const Unit& u, int wr, int wc, int fr, int fq, PG8_LAS unsigned char* lds, int wid, int lane) const {
;     ...
;             for (int m = 0; m < 4; ++m) { const int r = ai * HALF + wr * 64 + m * 16 + fr; const f32x2v sr = S[r]; const size_t off = (size_t)(u.pm * BM + r) * ldc + col0;
; #pragma unroll
;                 for (int bj = 0; bj < 2; ++bj)
; #pragma unroll
;                     for (int n = 0; n < 2; ++n) { const f32x4 bs = ai == 0 ? pre[m][bj][n] : *(const f32x4*)(base + off + bj * HALF + n * 16); f32x4 o = bs + cvv[bj][n] * (acc[ai][bj][m][n] * sr.y);
;                         if (bad) o = (f32x4){qnan, qnan, qnan, qnan}; *(f32x4*)(out + off + bj * HALF + n * 16) = o; }
	v_pk_mul_f32 v[62:63], v[62:63], v[88:89] op_sel:[0,1]
	v_pk_mul_f32 v[64:65], v[64:65], v[88:89] op_sel:[0,1]
	v_pk_mul_f32 v[58:59], v[58:59], v[88:89] op_sel:[0,1]
	v_pk_mul_f32 v[60:61], v[60:61], v[88:89] op_sel:[0,1]
	v_pk_mul_f32 v[54:55], v[54:55], v[88:89] op_sel:[0,1]
	v_pk_mul_f32 v[56:57], v[56:57], v[88:89] op_sel:[0,1]
	v_pk_mul_f32 v[46:47], v[46:47], v[88:89] op_sel:[0,1]
	v_pk_mul_f32 v[48:49], v[48:49], v[88:89] op_sel:[0,1]
	s_waitcnt vmcnt(15)
	v_pk_fma_f32 v[62:63], v[142:143], v[62:63], v[146:147]
	v_pk_fma_f32 v[64:65], v[144:145], v[64:65], v[148:149]
	v_cndmask_b32_e32 v62, v62, v126, vcc
	v_cndmask_b32_e32 v63, v63, v126, vcc
	v_cndmask_b32_e32 v64, v64, v126, vcc
	v_cndmask_b32_e32 v65, v65, v126, vcc
	global_store_dwordx4 v[72:73], v[62:65], off
	s_waitcnt vmcnt(15)
	v_pk_fma_f32 v[58:59], v[138:139], v[58:59], v[150:151]
	v_pk_fma_f32 v[60:61], v[140:141], v[60:61], v[152:153]
	v_cndmask_b32_e32 v58, v58, v126, vcc
	v_cndmask_b32_e32 v59, v59, v126, vcc
	v_cndmask_b32_e32 v60, v60, v126, vcc
	v_cndmask_b32_e32 v61, v61, v126, vcc
	global_store_dwordx4 v[72:73], v[58:61], off offset:64
	s_waitcnt vmcnt(15)
	v_pk_fma_f32 v[54:55], v[134:135], v[54:55], v[154:155]
	v_pk_fma_f32 v[56:57], v[136:137], v[56:57], v[156:157]
	v_cndmask_b32_e32 v54, v54, v126, vcc
	v_cndmask_b32_e32 v55, v55, v126, vcc
	v_cndmask_b32_e32 v56, v56, v126, vcc
	v_cndmask_b32_e32 v57, v57, v126, vcc
	global_store_dwordx4 v[72:73], v[54:57], off offset:512
	s_waitcnt vmcnt(15)
	v_pk_fma_f32 v[46:47], v[130:131], v[46:47], v[158:159]
	v_pk_fma_f32 v[48:49], v[132:133], v[48:49], v[160:161]
	v_cndmask_b32_e32 v46, v46, v126, vcc
	v_cndmask_b32_e32 v47, v47, v126, vcc
	v_cndmask_b32_e32 v48, v48, v126, vcc
	v_cndmask_b32_e32 v49, v49, v126, vcc
	global_store_dwordx4 v[72:73], v[46:49], off offset:576
	v_pk_mul_f32 v[50:51], v[50:51], v[90:91] op_sel:[0,1]
	v_pk_mul_f32 v[52:53], v[52:53], v[90:91] op_sel:[0,1]
	v_pk_mul_f32 v[42:43], v[42:43], v[90:91] op_sel:[0,1]
	v_pk_mul_f32 v[44:45], v[44:45], v[90:91] op_sel:[0,1]
	v_pk_mul_f32 v[38:39], v[38:39], v[90:91] op_sel:[0,1]
	v_pk_mul_f32 v[40:41], v[40:41], v[90:91] op_sel:[0,1]
	v_pk_mul_f32 v[30:31], v[30:31], v[90:91] op_sel:[0,1]
	v_pk_mul_f32 v[32:33], v[32:33], v[90:91] op_sel:[0,1]
	s_waitcnt vmcnt(15)
	v_pk_fma_f32 v[50:51], v[142:143], v[50:51], v[162:163]
	v_pk_fma_f32 v[52:53], v[144:145], v[52:53], v[164:165]
	v_cndmask_b32_e32 v50, v50, v126, vcc
	v_cndmask_b32_e32 v51, v51, v126, vcc
	v_cndmask_b32_e32 v52, v52, v126, vcc
	v_cndmask_b32_e32 v53, v53, v126, vcc
	global_store_dwordx4 v[76:77], v[50:53], off
	s_waitcnt vmcnt(15)
	v_pk_fma_f32 v[42:43], v[138:139], v[42:43], v[166:167]
	v_pk_fma_f32 v[44:45], v[140:141], v[44:45], v[168:169]
	v_cndmask_b32_e32 v42, v42, v126, vcc
	v_cndmask_b32_e32 v43, v43, v126, vcc
	v_cndmask_b32_e32 v44, v44, v126, vcc
	v_cndmask_b32_e32 v45, v45, v126, vcc
	global_store_dwordx4 v[76:77], v[42:45], off offset:64
	s_waitcnt vmcnt(15)
	v_pk_fma_f32 v[38:39], v[134:135], v[38:39], v[170:171]
	v_pk_fma_f32 v[40:41], v[136:137], v[40:41], v[172:173]
	v_cndmask_b32_e32 v38, v38, v126, vcc
	v_cndmask_b32_e32 v39, v39, v126, vcc
	v_cndmask_b32_e32 v40, v40, v126, vcc
	v_cndmask_b32_e32 v41, v41, v126, vcc
	global_store_dwordx4 v[76:77], v[38:41], off offset:512
	s_waitcnt vmcnt(15)
;     __device__ __forceinline__ void fused(f32x4 (&acc)[2][2][4][2], const Unit& u, int wr, int wc, int fr, int fq, PG8_LAS unsigned char* lds, int wid, int lane) const {
;     ...
;             for (int m = 0; m < 4; ++m) { const int r = ai * HALF + wr * 64 + m * 16 + fr; const f32x2v sr = S[r]; const size_t off = (size_t)(u.pm * BM + r) * ldc + col0;
; #pragma unroll
;                 for (int bj = 0; bj < 2; ++bj)
; #pragma unroll
;                     for (int n = 0; n < 2; ++n) { const f32x4 bs = ai == 0 ? pre[m][bj][n] : *(const f32x4*)(base + off + bj * HALF + n * 16); f32x4 o = bs + cvv[bj][n] * (acc[ai][bj][m][n] * sr.y);
;                         if (bad) o = (f32x4){qnan, qnan, qnan, qnan}; *(f32x4*)(out + off + bj * HALF + n * 16) = o; }
	v_pk_fma_f32 v[30:31], v[130:131], v[30:31], v[174:175]
	v_pk_fma_f32 v[32:33], v[132:133], v[32:33], v[176:177]
	v_cndmask_b32_e32 v30, v30, v126, vcc
	v_cndmask_b32_e32 v31, v31, v126, vcc
	v_cndmask_b32_e32 v32, v32, v126, vcc
	v_cndmask_b32_e32 v33, v33, v126, vcc
	global_store_dwordx4 v[76:77], v[30:33], off offset:576
	v_pk_mul_f32 v[34:35], v[34:35], v[92:93] op_sel:[0,1]
	v_pk_mul_f32 v[36:37], v[36:37], v[92:93] op_sel:[0,1]
	v_pk_mul_f32 v[26:27], v[26:27], v[92:93] op_sel:[0,1]
	v_pk_mul_f32 v[28:29], v[28:29], v[92:93] op_sel:[0,1]
	v_pk_mul_f32 v[22:23], v[22:23], v[92:93] op_sel:[0,1]
	v_pk_mul_f32 v[24:25], v[24:25], v[92:93] op_sel:[0,1]
	v_pk_mul_f32 v[14:15], v[14:15], v[92:93] op_sel:[0,1]
	v_pk_mul_f32 v[16:17], v[16:17], v[92:93] op_sel:[0,1]
	s_waitcnt vmcnt(15)
	v_pk_fma_f32 v[34:35], v[142:143], v[34:35], v[178:179]
	v_pk_fma_f32 v[36:37], v[144:145], v[36:37], v[180:181]
	v_cndmask_b32_e32 v34, v34, v126, vcc
	v_cndmask_b32_e32 v35, v35, v126, vcc
	v_cndmask_b32_e32 v36, v36, v126, vcc
	v_cndmask_b32_e32 v37, v37, v126, vcc
	global_store_dwordx4 v[80:81], v[34:37], off
	s_waitcnt vmcnt(15)
	v_pk_fma_f32 v[26:27], v[138:139], v[26:27], v[182:183]
	v_pk_fma_f32 v[28:29], v[140:141], v[28:29], v[184:185]
	v_cndmask_b32_e32 v26, v26, v126, vcc
	v_cndmask_b32_e32 v27, v27, v126, vcc
	v_cndmask_b32_e32 v28, v28, v126, vcc
	v_cndmask_b32_e32 v29, v29, v126, vcc
	global_store_dwordx4 v[80:81], v[26:29], off offset:64
	s_waitcnt vmcnt(15)
	v_pk_fma_f32 v[22:23], v[134:135], v[22:23], v[186:187]
	v_pk_fma_f32 v[24:25], v[136:137], v[24:25], v[188:189]
	v_cndmask_b32_e32 v22, v22, v126, vcc
	v_cndmask_b32_e32 v23, v23, v126, vcc
	v_cndmask_b32_e32 v24, v24, v126, vcc
	v_cndmask_b32_e32 v25, v25, v126, vcc
	global_store_dwordx4 v[80:81], v[22:25], off offset:512
	s_waitcnt vmcnt(15)
	v_pk_fma_f32 v[14:15], v[130:131], v[14:15], v[190:191]
	v_pk_fma_f32 v[16:17], v[132:133], v[16:17], v[192:193]
	v_cndmask_b32_e32 v14, v14, v126, vcc
	v_cndmask_b32_e32 v15, v15, v126, vcc
	v_cndmask_b32_e32 v16, v16, v126, vcc
	v_cndmask_b32_e32 v17, v17, v126, vcc
	global_store_dwordx4 v[80:81], v[14:17], off offset:576
	v_pk_mul_f32 v[18:19], v[18:19], v[94:95] op_sel:[0,1]
	v_pk_mul_f32 v[20:21], v[20:21], v[94:95] op_sel:[0,1]
	v_pk_mul_f32 v[10:11], v[10:11], v[94:95] op_sel:[0,1]
	v_pk_mul_f32 v[12:13], v[12:13], v[94:95] op_sel:[0,1]
	v_pk_mul_f32 v[6:7], v[6:7], v[94:95] op_sel:[0,1]
	v_pk_mul_f32 v[8:9], v[8:9], v[94:95] op_sel:[0,1]
	v_pk_mul_f32 v[2:3], v[2:3], v[94:95] op_sel:[0,1]
	v_pk_mul_f32 v[4:5], v[4:5], v[94:95] op_sel:[0,1]
	s_waitcnt vmcnt(15)
	v_pk_fma_f32 v[18:19], v[142:143], v[18:19], v[194:195]
	v_pk_fma_f32 v[20:21], v[144:145], v[20:21], v[196:197]
	v_cndmask_b32_e32 v18, v18, v126, vcc
	v_cndmask_b32_e32 v19, v19, v126, vcc
	v_cndmask_b32_e32 v20, v20, v126, vcc
	v_cndmask_b32_e32 v21, v21, v126, vcc
	global_store_dwordx4 v[84:85], v[18:21], off
	s_waitcnt vmcnt(15)
	v_pk_fma_f32 v[10:11], v[138:139], v[10:11], v[198:199]
	v_pk_fma_f32 v[12:13], v[140:141], v[12:13], v[200:201]
	v_cndmask_b32_e32 v10, v10, v126, vcc
	v_cndmask_b32_e32 v11, v11, v126, vcc
	v_cndmask_b32_e32 v12, v12, v126, vcc
	v_cndmask_b32_e32 v13, v13, v126, vcc
	global_store_dwordx4 v[84:85], v[10:13], off offset:64
	s_waitcnt vmcnt(15)
	v_pk_fma_f32 v[6:7], v[134:135], v[6:7], v[202:203]
	v_pk_fma_f32 v[8:9], v[136:137], v[8:9], v[204:205]
	v_cndmask_b32_e32 v6, v6, v126, vcc
	v_cndmask_b32_e32 v7, v7, v126, vcc
	v_cndmask_b32_e32 v8, v8, v126, vcc
	v_cndmask_b32_e32 v9, v9, v126, vcc
	global_store_dwordx4 v[84:85], v[6:9], off offset:512
	s_waitcnt vmcnt(15)
	v_pk_fma_f32 v[2:3], v[130:131], v[2:3], v[206:207]
	v_pk_fma_f32 v[4:5], v[132:133], v[4:5], v[208:209]
	v_cndmask_b32_e32 v2, v2, v126, vcc
	v_cndmask_b32_e32 v3, v3, v126, vcc
	v_cndmask_b32_e32 v4, v4, v126, vcc
	v_cndmask_b32_e32 v5, v5, v126, vcc
	global_store_dwordx4 v[84:85], v[2:5], off offset:576
